# v33 with P5 x loads back to default + hgC loop touches one x line per thread per item (on-die prefetch of the P5 residual during P4)
# baseline (speedup 1.0000x reference)
; __device__ __forceinline__ void hgC_loop(Frame& F, unsigned* ctr) {
;     ...
;         if (nxt < 1024) HGC_FETCH(nxt);
.LBB0_697:
	s_or_b64 exec, exec, s[20:21]
	s_cmpk_lt_i32 s16, 0x400
	s_cselect_b64 s[22:23], -1, 0
	s_cmpk_gt_i32 s16, 0x3ff
	s_cselect_b64 s[20:21], -1, 0
	s_waitcnt vmcnt(4)
	v_mov_b64_e32 v[48:49], v[8:9]
	v_mov_b64_e32 v[42:43], v[50:51]
	s_and_b64 vcc, exec, s[20:21]
	s_waitcnt vmcnt(0)
	v_mov_b64_e32 v[88:89], v[70:71]
	v_mov_b64_e32 v[86:87], v[76:77]
	v_mov_b64_e32 v[84:85], v[78:79]
	v_mov_b64_e32 v[82:83], v[80:81]
	v_mov_b64_e32 v[46:47], v[6:7]
	v_mov_b64_e32 v[44:45], v[52:53]
	s_cbranch_vccnz .LBB0_699
	v_readlane_b32 s26, v238, 4
	v_readlane_b32 s27, v238, 5
	v_lshlrev_b32_e32 v2, 7, v0
	s_lshl_b32 s24, s16, 16
	s_add_u32 s26, s26, s24
	s_addc_u32 s27, s27, 0
	global_load_dword v239, v2, s[26:27]
	s_ashr_i32 s17, s16, 31
	s_lshl_b64 s[24:25], s[16:17], 15
	v_lshl_add_u64 v[2:3], v[64:65], 0, s[24:25]
	v_lshl_add_u64 v[4:5], v[2:3], 0, v[56:57]
	s_lshl_b64 s[26:27], s[16:17], 14
	v_lshl_add_u64 v[10:11], v[2:3], 0, v[58:59]
	global_load_dwordx4 v[18:21], v[4:5], off
	global_load_dwordx4 v[22:25], v[10:11], off
	v_lshl_add_u64 v[4:5], v[2:3], 0, v[60:61]
	v_lshl_add_u64 v[2:3], v[2:3], 0, v[62:63]
	s_lshl_b32 s10, s16, 4
	s_lshl_b32 s13, s16, 6
	global_load_dwordx4 v[26:29], v[4:5], off
	global_load_dwordx4 v[30:33], v[2:3], off
	v_lshl_add_u64 v[2:3], v[66:67], 0, s[26:27]
	s_and_b32 s10, s10, 0xfffff800
	v_lshl_add_u64 v[4:5], v[2:3], 0, v[56:57]
	v_lshl_add_u64 v[2:3], v[2:3], 0, v[58:59]
	s_and_b32 s13, s13, 0x7c0
	global_load_dwordx4 v[34:37], v[4:5], off
	global_load_dwordx4 v[38:41], v[2:3], off
	v_lshl_add_u64 v[2:3], v[68:69], 0, s[26:27]
	s_or_b32 s10, s10, s13
	global_load_dwordx4 v[42:45], v[2:3], off offset:16
	global_load_dwordx4 v[46:49], v[2:3], off
	v_add_u32_e32 v2, s10, v90
	v_ashrrev_i32_e32 v3, 31, v2
	v_lshlrev_b64 v[2:3], 12, v[2:3]
	s_lshl_b32 s10, s16, 3
	v_lshl_add_u64 v[2:3], s[56:57], 0, v[2:3]
	s_and_b32 s10, s10, 0x300
	v_lshl_add_u64 v[2:3], v[2:3], 0, s[10:11]
	s_mov_b32 s13, s11
	v_lshl_add_u64 v[2:3], v[2:3], 0, s[12:13]
	v_mov_b32_e32 v75, v55
	v_lshl_add_u64 v[2:3], v[2:3], 0, v[74:75]
	global_load_dwordx2 v[82:83], v[2:3], off offset:3072
	global_load_dwordx2 v[84:85], v[2:3], off offset:3088
	global_load_dwordx2 v[86:87], v[2:3], off offset:3104
	global_load_dwordx2 v[88:89], v[2:3], off offset:3120
